# MLA up-projection units scheduled by the XCD-grouped block index (same-XCD CUs share an A row-panel in L2)
# speedup vs baseline: 1.0092x; 1.0092x over previous
; __global__ void __launch_bounds__(512, 2) fwd_megakernel(Args a) {
;     ...
;     unsigned char* ws = a.ws;
;     LAS unsigned char* ldsl = (LAS unsigned char*)lds;
;     LAS float* scr = (LAS float*)(ldsl + wave * 16384);
;     float* mod = (float*)(ws + WS_MOD); float* CX = (float*)(ws + WS_CX);
;     bf16_t* H = (bf16_t*)(ws + WS_H); bf16_t* Z = (bf16_t*)(ws + WS_Z); bf16_t* QC = (bf16_t*)(ws + WS_H); bf16_t* KVC = (bf16_t*)(ws + WS_KVC);
;     bf16_t* Y = (bf16_t*)(ws + WS_KVC); bf16_t* O = (bf16_t*)(ws + WS_O); bf16_t* T = (bf16_t*)(ws + WS_T); bf16_t* U = (bf16_t*)(ws + WS_U); bf16_t* TP = (bf16_t*)(ws + WS_TP);
;     unsigned* barw = (unsigned*)(ws + WS_BAR);
;     volatile LAS unsigned* bst = (volatile LAS unsigned*)(ldsl + 131072 + 64);
;     if (bid == 0) for (int i = tid; i < XCD_BAR_WORDS; i += 512) barw[i] = 0u;
;     if (tid < 2) bst[tid] = 0u;
;     __syncthreads();
;     mod_phase(a, lds, bid, G, tid);
;     convert_weights(a, 0, gw, NGW, lane, scr);
;     grid.sync();
;     const XcdBarrier xb = xcd_barrier_post(barw, bst);
;     ...
;     row_phase<false, true>(bid, G, MTOT, a.in[I_X], a.in[I_CTX], nullptr, nullptr, nullptr, nullptr, nullptr, 0, nullptr, a.in[I_GPRE1], mod, 0, 2048, H, ws + WS_H8, lds);
;     GSYNC();
;     for (int l = 0; l < 2; ++l) {
;         const bool ctx_out = (l == 0);
;         const int nMr = ctx_out ? MTOT / 256 : NLAT / 256;
;         const float* modL = mod + (size_t)l * 9 * MODW;
;         { pg8::TileSched S; S.nM = ctx_out ? MTOT / 256 : NLAT / 256; S.nN = 23; S.nwg = S.nM * S.nN; S.G = G; S.c = bid; S.nsub = 1; S.A = (const char*)H; S.B = (const char*)(ws + WS_WIN);
;           S.aT = (size_t)256 * DM * 2; S.bT = (size_t)256 * DM * 2; S.aS = 0; S.bS = 0; S.nx = ctx_out ? 0 : 104;
;           S.pn_split = 16; S.pn_skip = 24; S.pn_boff = 0;
;           pg8::EpiZ E{Z}; pg8::gemm_phase(ldsl, DM, DM, DM, S, E); }
;         { pg8::TileSched S; S.nM = ctx_out ? MTOT / 256 : NLAT / 256; S.nN = 24; S.nwg = S.nM * S.nN; S.G = G; S.c = bid; S.nsub = 1; S.A = (const char*)(ws + WS_H8); S.B = (const char*)(ws + WS_WG8);
;           S.aT = (size_t)256 * DM; S.bT = (size_t)256 * DM; S.aS = 0; S.bS = 0; S.nx = 0; S.pn_split = 0; S.pn_skip = 16; S.pn_boff = 16;
;           pg8::EpiZ8 E{Z}; pg8::gemm_phase<true>(ldsl, DM / 2, DM / 2, DM / 2, S, E); }
;         GSYNC();
;         prep_phase(a, l, gw, NGW, lane);
;         GSYNC();
.LBB0_205:
	v_writelane_b32 v251, s52, 12
	s_nop 1
	v_writelane_b32 v251, s53, 13
	v_writelane_b32 v251, s34, 14
	s_nop 1
	v_writelane_b32 v251, s35, 15
	s_or_b64 exec, exec, s[0:1]
	s_load_dwordx2 s[8:9], s[70:71], 0xd0
	s_waitcnt lgkmcnt(0)
	s_barrier
	s_load_dwordx2 s[20:21], s[70:71], 0xd0
	s_add_u32 s0, s8, 0x100000
	s_addc_u32 s1, s9, 0
	s_add_u32 s64, s8, 0xe180000
	s_addc_u32 s65, s9, 0
	s_add_u32 s66, s8, 0x281c0000
	v_writelane_b32 v251, s0, 16
	s_addc_u32 s67, s9, 0
	s_load_dwordx16 s[76:91], s[70:71], 0x30
	v_writelane_b32 v251, s1, 17
	s_add_u32 s0, s8, 0x2cc00000
	s_addc_u32 s1, s9, 0
	s_add_u32 s16, s8, 0x17180000
	v_writelane_b32 v251, s0, 18
	s_addc_u32 s17, s9, 0
	s_load_dwordx8 s[36:43], s[70:71], 0x70
	v_writelane_b32 v251, s1, 19
	s_add_u32 s0, s8, 0x23780000
	s_addc_u32 s1, s9, 0
	v_writelane_b32 v251, s0, 20
	s_mov_b32 s45, 0
	s_brev_b32 s46, 31
	v_writelane_b32 v251, s1, 21
	s_add_u32 s0, s8, 0x1100000
	v_writelane_b32 v251, s0, 22
	s_addc_u32 s0, s9, 0
	s_ashr_i32 s92, s2, 31
	v_writelane_b32 v251, s0, 23
	s_lshr_b32 s0, s92, 29
	s_add_i32 s0, s2, s0
	s_ashr_i32 s15, s0, 3
	s_and_b32 s0, s0, -8
	s_sub_i32 s18, s2, s0
	s_add_u32 s0, s8, 0x35c00000
	v_writelane_b32 v251, s0, 24
	s_addc_u32 s0, s9, 0
	v_writelane_b32 v251, s0, 25
	s_add_u32 s0, s8, 0xdc200
	s_addc_u32 s1, s9, 0
	v_writelane_b32 v251, s0, 26
	v_mov_b32_e32 v1, 0
	v_mov_b32_e32 v236, 0x7c7c7c7c
	v_writelane_b32 v251, s1, 27
	s_add_u32 s0, s8, 0xdc400
	s_addc_u32 s1, s9, 0
	v_writelane_b32 v251, s0, 28
	v_mov_b32_e32 v237, 0x1000
	v_mov_b32_e32 v238, 0x2000
	v_writelane_b32 v251, s1, 29
	s_add_u32 s0, s8, 0xdc500
	s_addc_u32 s1, s9, 0
	v_writelane_b32 v251, s0, 30
	v_mov_b32_e32 v239, 1
	v_mov_b32_e32 v198, 0x358637bd
	v_writelane_b32 v251, s1, 31
	s_add_u32 s0, s8, 0xdc600
	s_addc_u32 s1, s9, 0
	v_writelane_b32 v251, s0, 32
	v_mov_b32_e32 v240, 0x1080
	v_mov_b32_e32 v241, 0x5c80
	v_writelane_b32 v251, s1, 33
	s_add_u32 s0, s8, 0xdc700
	s_addc_u32 s1, s9, 0
	v_writelane_b32 v251, s0, 34
	v_mov_b32_e32 v242, 0xf149f2ca
	v_mov_b64_e32 v[200:201], 0x200
	v_writelane_b32 v251, s1, 35
	s_add_u32 s0, s8, 0xdc800
	s_addc_u32 s1, s9, 0
	v_writelane_b32 v251, s0, 36
	v_mov_b32_e32 v243, 0xc000
	s_mov_b32 s58, 0xfd000000
	v_writelane_b32 v251, s1, 37
	s_add_u32 s0, s8, 0xdc900
	s_addc_u32 s1, s9, 0
	v_writelane_b32 v251, s0, 38
	s_mov_b32 s59, 0xfd001000
	s_mov_b32 s63, 0xfd800000
	v_writelane_b32 v251, s1, 39
	s_add_u32 s0, s8, 0xdca00
	s_addc_u32 s1, s9, 0
	v_writelane_b32 v251, s0, 40
	s_mov_b64 s[68:69], 0x10000
	s_mov_b32 s47, -1
	v_writelane_b32 v251, s1, 41
	s_add_u32 s0, s8, 0xdcb00
	s_addc_u32 s1, s9, 0
	v_writelane_b32 v251, s0, 42
	s_nop 1
	v_writelane_b32 v251, s1, 43
	s_add_u32 s0, s8, 0xdcc00
	s_addc_u32 s1, s9, 0
	v_writelane_b32 v251, s0, 44
	s_nop 1
	v_writelane_b32 v251, s1, 45
	s_add_u32 s0, s8, 0xdcd00
	s_addc_u32 s1, s9, 0
	v_writelane_b32 v251, s0, 46
	s_nop 1
	v_writelane_b32 v251, s1, 47
	s_add_u32 s0, s8, 0xdce00
	s_addc_u32 s1, s9, 0
	v_writelane_b32 v251, s0, 48
	s_nop 1
	v_writelane_b32 v251, s1, 49
	s_add_u32 s0, s8, 0xdcf00
	s_addc_u32 s1, s9, 0
	v_writelane_b32 v251, s0, 50
	s_nop 1
	v_writelane_b32 v251, s1, 51
	s_add_u32 s0, s8, 0xdd000
	s_addc_u32 s1, s9, 0
	v_writelane_b32 v251, s0, 52
	s_nop 1
	v_writelane_b32 v251, s1, 53
	s_add_u32 s0, s8, 0xdd100
	s_addc_u32 s1, s9, 0
	v_writelane_b32 v251, s0, 54
	s_nop 1
	v_writelane_b32 v251, s1, 55
	s_add_u32 s0, s8, 0xdd200
	s_addc_u32 s1, s9, 0
	v_writelane_b32 v251, s0, 56
	s_nop 1
	v_writelane_b32 v251, s1, 57
	s_add_u32 s0, s8, 0xdd300
	s_addc_u32 s1, s9, 0
	v_writelane_b32 v251, s0, 58
	s_nop 1
	v_writelane_b32 v251, s1, 59
	s_add_u32 s0, s8, 0xdf400
	s_addc_u32 s1, s9, 0
	v_writelane_b32 v251, s0, 60
	s_nop 1
	v_writelane_b32 v251, s1, 61
	s_add_u32 s0, s8, 0xdf500
	s_addc_u32 s1, s9, 0
	s_waitcnt lgkmcnt(0)
	s_add_u32 s28, s20, 0xe180000
	s_addc_u32 s29, s21, 0
	v_writelane_b32 v251, s0, 62
	s_cmpk_lt_i32 s72, 0x2400
	s_nop 0
	v_writelane_b32 v251, s1, 63
	s_cselect_b64 s[0:1], -1, 0
	v_writelane_b32 v252, s0, 0
	v_readlane_b32 s14, v251, 0
	s_nop 0
	s_cmpk_lt_i32 s14, 0x1b0
	v_writelane_b32 v252, s1, 1
	s_cselect_b64 s[0:1], -1, 0
	v_writelane_b32 v252, s0, 2
	s_cmpk_gt_i32 s14, 0x1af
	s_nop 0
	v_writelane_b32 v252, s1, 3
	s_cselect_b64 s[0:1], -1, 0
	v_writelane_b32 v252, s0, 4
	s_nop 1
	v_writelane_b32 v252, s1, 5
	s_add_i32 s0, s14, 0xfffffe50
	s_cmpk_lt_u32 s0, 0x240
	s_cselect_b64 s[4:5], -1, 0
	v_writelane_b32 v252, s4, 6
	s_lshr_b32 s0, s0, 3
	s_nop 0
	v_writelane_b32 v252, s5, 7
	v_writelane_b32 v252, s0, 8
	s_mul_hi_i32 s0, s14, 0x2aaaaaab
	s_lshr_b32 s1, s0, 31
	s_add_i32 s0, s0, s1
	v_writelane_b32 v252, s0, 9
	s_mul_i32 s0, s0, -6
	s_add_i32 s0, s0, s14
	v_writelane_b32 v252, s0, 10
	s_and_b32 s0, s14, 7
	v_writelane_b32 v252, s0, 11
	s_add_u32 s0, s20, 0x9980000
	v_writelane_b32 v252, s0, 12
	s_addc_u32 s0, s21, 0
	v_writelane_b32 v252, s0, 13
	s_add_u32 s0, s20, 0x281c0000
	v_writelane_b32 v252, s0, 14
	s_addc_u32 s0, s21, 0
	v_writelane_b32 v252, s0, 15
	s_add_u32 s0, s20, 0x2cc00000
	v_writelane_b32 v252, s0, 16
	s_addc_u32 s0, s21, 0
	s_cmpk_lt_i32 s14, 0x200
	v_writelane_b32 v252, s0, 17
	s_cselect_b64 s[0:1], -1, 0
	v_writelane_b32 v252, s0, 18
	s_nop 1
	v_writelane_b32 v252, s1, 19
	s_add_u32 s0, s20, 0xe185000
	v_writelane_b32 v252, s0, 20
	s_addc_u32 s0, s21, 0
	v_writelane_b32 v252, s0, 21
	s_add_u32 s0, s20, 0xe185200
	v_writelane_b32 v252, s0, 22
	s_addc_u32 s0, s21, 0
	v_writelane_b32 v252, s0, 23
	s_add_u32 s0, s20, 0xe185c00
	s_addc_u32 s1, s21, 0
	v_writelane_b32 v252, s0, 24
	s_nop 1
	v_writelane_b32 v252, s1, 25
	s_add_u32 s0, s20, 0xe180800
; #define GSYNC() xcd_barrier(xb)
; __device__ __forceinline__ TItem titem_get(const Args& a, int l, int it) {
;     unsigned char* ws = a.ws; TItem d;
;     constexpr int I_IN = 32 * 370, I_13 = 32 * 176, I_2 = 88 * 64, I_O = 32 * 64, I_BR = 16 * 64, I_UQ = 8 * 48;
;     int r = it; d.mode13 = false; d.gate8 = false;
; __global__ void __launch_bounds__(512, 2) fwd_megakernel(Args a) {
;     ...
;         if (ctx_out) { pg8::CtxSplitSched S; S.G = G; S.c = bid; S.A = (const char*)Y; S.B = (const char*)(ws + WS_WO); S.aT = (size_t)256 * DM * 2; S.bT = (size_t)256 * DM * 2; S.kqB = (size_t)(DM / 4) * 2;
;           pg8::EpiSlab E{TP}; pg8::gemm_phase(ldsl, DM, DM, DM / 4, S, E); }
;         GSYNC();
;         if (l == 0) row_phase<true, true, false, true>(bid, G, MTOT, a.in[I_X], a.in[I_CTX], O, CX, T, ctx_out ? TP : nullptr, modL, 4096, a.in[I_GPOST1] + l * DM,
;                               a.in[I_GPRE2] + l * DM, modL, 6144, 8192, H, nullptr, lds);
;         else        row_phase<true, true, true, true>(bid, G, NLAT, a.out, a.in[I_CTX], O, CX, T, ctx_out ? TP : nullptr, modL, 4096, a.in[I_GPOST1] + l * DM,
;                               a.in[I_GPRE2] + l * DM, modL, 6144, 8192, H, nullptr, lds);
;         GSYNC();
;         { pg8::TileSched S; S.nM = nMr; S.nN = 2 * DFF / 256; S.nwg = S.nM * S.nN; S.G = G; S.c = bid; S.nsub = 1; S.A = (const char*)H; S.B = (const char*)(ws + WS_W13);
;           S.aT = (size_t)256 * DM * 2; S.bT = (size_t)256 * DM * 2; S.aS = 0; S.bS = 0; S.nx = 0; S.pn_split = 1 << 30; S.pn_skip = 0; S.pn_boff = 0;
;           pg8::EpiSwiglu E{U}; pg8::gemm_phase(ldsl, DM, DM, DM, S, E); }
;         GSYNC();
;         { pg8::TileSched S; S.nM = NLAT / 256; S.nN = 8; S.nwg = S.nM * S.nN; S.G = G; S.c = bid; S.nsub = 1; S.A = (const char*)U; S.B = (const char*)(ws + WS_W2);
;           S.aT = (size_t)256 * DFF * 2; S.bT = (size_t)256 * DFF * 2; S.aS = 0; S.bS = 0; S.nx = 0; S.pn_split = 1 << 30; S.pn_skip = 0; S.pn_boff = 0;
;           pg8::EpiQKV E{T, T, DM, DM}; pg8::gemm_phase(ldsl, DFF, DFF, DFF, S, E); }
;         if (ctx_out) { pg8::CtxSplitSched S; S.G = G; S.c = bid; S.A = (const char*)U; S.B = (const char*)(ws + WS_W2); S.aT = (size_t)256 * DFF * 2; S.bT = (size_t)256 * DFF * 2; S.kqB = (size_t)(DFF / 4) * 2;
;           pg8::EpiSlab E{TP}; pg8::gemm_phase(ldsl, DFF, DFF, DFF / 4, S, E); }
	v_writelane_b32 v252, s0, 26
	s_addc_u32 s0, s21, 0
	v_writelane_b32 v252, s0, 27
	s_add_u32 s0, s20, 0xe181000
	v_writelane_b32 v252, s0, 28
	s_addc_u32 s0, s21, 0
	s_cmpk_lt_i32 s14, 0xc0
	v_writelane_b32 v252, s0, 29
	s_cselect_b64 s[0:1], -1, 0
	v_writelane_b32 v252, s0, 30
	s_nop 1
	v_writelane_b32 v252, s1, 31
	s_add_u32 s0, s8, 0x4380000
	v_writelane_b32 v252, s0, 32
	s_addc_u32 s0, s9, 0
	s_add_u32 s19, s8, 0x4f80000
	s_addc_u32 s22, s9, 0
	s_cmpk_lt_i32 s2, 0x200
	v_writelane_b32 v252, s0, 33
	s_cselect_b64 s[0:1], -1, 0
	v_writelane_b32 v252, s0, 34
	s_nop 1
	v_writelane_b32 v252, s1, 35
	s_lshl_b32 s0, s18, 6
	s_cmpk_lt_i32 s2, 0x100
	s_cselect_b64 s[4:5], -1, 0
	s_ashr_i32 s1, s2, 5
	s_add_i32 s10, s1, 64
	v_writelane_b32 v252, s4, 36
	s_ashr_i32 s11, s10, 31
	s_bfe_u32 s7, s2, 0x30002
	s_and_b32 s12, s2, 3
	v_writelane_b32 v252, s5, 37
	s_lshl_b32 s1, s12, 10
	s_lshl_b32 s3, s7, 20
	s_lshl_b64 s[4:5], s[10:11], 20
	s_add_u32 s3, s19, s3
	s_addc_u32 s6, s22, 0
	s_add_u32 s24, s3, s1
	s_addc_u32 s25, s6, 0
	s_add_u32 s3, s66, s4
	s_addc_u32 s4, s67, s5
	s_add_u32 s26, s24, 0x80000
	s_addc_u32 s27, s25, 0
	v_writelane_b32 v252, s26, 38
	s_nop 1
	v_writelane_b32 v252, s27, 39
	s_add_u32 s26, s3, s1
	s_addc_u32 s27, s4, 0
	s_add_u32 s4, s26, 0x80000
	v_writelane_b32 v252, s26, 40
	s_addc_u32 s5, s27, 0
	s_mul_i32 s1, s7, 0x2c0000
	v_writelane_b32 v252, s27, 41
	v_writelane_b32 v252, s4, 42
	s_mul_i32 s3, s12, 0xb00
	s_nop 0
	v_writelane_b32 v252, s5, 43
	s_add_u32 s4, s24, 0x80080
	v_writelane_b32 v252, s24, 44
	s_addc_u32 s5, s25, 0
	s_nop 0
	v_writelane_b32 v252, s25, 45
	v_writelane_b32 v252, s4, 46
	s_nop 1
	v_writelane_b32 v252, s5, 47
	s_add_u32 s4, s78, 0x2000
	s_addc_u32 s5, s79, 0
	v_writelane_b32 v252, s4, 48
	s_nop 1
	v_writelane_b32 v252, s5, 49
	s_add_u32 s4, s80, 0x2000
	s_addc_u32 s5, s81, 0
	s_add_u32 s23, s8, 0x5780000
	s_addc_u32 s24, s9, 0
	s_add_u32 s25, s8, 0x8380000
	s_addc_u32 s26, s9, 0
	v_writelane_b32 v252, s4, 50
	s_add_u32 s1, s25, s1
	s_nop 0
	v_writelane_b32 v252, s5, 51
	s_addc_u32 s4, s26, 0
	v_writelane_b32 v252, s7, 52
	s_add_u32 s6, s1, s3
	v_writelane_b32 v252, s12, 53
	s_addc_u32 s7, s4, 0
	s_mov_b32 s4, s10
	s_mul_i32 s1, s10, 0x2c0000
	v_writelane_b32 v252, s4, 54
	s_add_u32 s1, s16, s1
	s_nop 0
	v_writelane_b32 v252, s5, 55
	s_mul_hi_i32 s4, s10, 0x2c0000
	s_addc_u32 s4, s17, s4
	s_add_u32 s10, s6, 0x160000
	s_addc_u32 s11, s7, 0
	v_writelane_b32 v252, s10, 56
	s_nop 1
	v_writelane_b32 v252, s11, 57
	s_add_u32 s10, s1, s3
	s_addc_u32 s11, s4, 0
	s_add_u32 s4, s10, 0x160000
	v_writelane_b32 v252, s10, 58
	s_addc_u32 s5, s11, 0
	s_nop 0
	v_writelane_b32 v252, s11, 59
	v_writelane_b32 v252, s4, 60
	s_nop 1
	v_writelane_b32 v252, s5, 61
	s_add_u32 s4, s6, 0x160080
	v_writelane_b32 v252, s6, 62
	s_addc_u32 s5, s7, 0
	v_writelane_b32 v253, s4, 0
	v_writelane_b32 v252, s7, 63
	s_nop 0
	v_writelane_b32 v253, s5, 1
	s_add_u32 s4, s82, 0x2000
	s_addc_u32 s5, s83, 0
	v_writelane_b32 v253, s4, 2
	s_nop 1
	v_writelane_b32 v253, s5, 3
	s_add_u32 s4, s76, 0x2000
	s_addc_u32 s5, s77, 0
	s_add_u32 s1, s8, 0x6c000
	s_addc_u32 s3, s9, 0
	v_writelane_b32 v253, s4, 4
	s_cmpk_gt_i32 s72, 0x2e3f
	s_nop 0
	v_writelane_b32 v253, s5, 5
	s_cselect_b64 s[4:5], -1, 0
	v_writelane_b32 v253, s4, 6
	s_cmpk_gt_u32 s72, 0x5a3f
	s_nop 0
	v_writelane_b32 v253, s5, 7
	s_cselect_b64 s[4:5], -1, 0
	v_writelane_b32 v253, s4, 8
	s_cmpk_gt_u32 s72, 0x703f
	s_nop 0
	v_writelane_b32 v253, s5, 9
	s_cselect_b64 s[4:5], -1, 0
	v_writelane_b32 v253, s4, 10
	s_cmpk_gt_u32 s72, 0x783f
	s_nop 0
	v_writelane_b32 v253, s5, 11
	s_cselect_b64 s[4:5], -1, 0
	v_writelane_b32 v253, s4, 12
	s_cmpk_lt_u32 s72, 0x8440
	s_nop 0
	v_writelane_b32 v253, s5, 13
	s_cselect_b64 s[4:5], -1, 0
	v_writelane_b32 v253, s4, 14
	s_cmpk_lt_u32 s72, 0x85c0
	s_nop 0
	v_writelane_b32 v253, s5, 15
	s_cselect_b64 s[4:5], -1, 0
	s_and_b32 s6, s72, 0x7fffffc0
	s_add_i32 s6, s6, 0xffff7a40
	s_add_u32 s30, s42, 0x400000
	s_addc_u32 s31, s43, 0
	s_add_i32 s7, s72, 0x7bc0
	s_and_b32 s8, s7, 0xffff
	s_mul_i32 s8, s8, 0xaaab
	s_lshr_b32 s8, s8, 21
	s_mul_i32 s9, s8, 48
	s_sub_i32 s9, s7, s9
	s_lshl_b32 s7, s72, 5
	s_and_b32 s27, s7, 0x7e0
	s_add_u32 s34, s40, 0x300000
	v_writelane_b32 v253, s36, 16
	s_addc_u32 s35, s41, 0
	s_lshl_b32 s7, s8, 6
	v_writelane_b32 v253, s37, 17
	v_writelane_b32 v253, s38, 18
	v_writelane_b32 v253, s39, 19
	v_writelane_b32 v253, s40, 20
	v_writelane_b32 v253, s41, 21
	v_writelane_b32 v253, s42, 22
	s_lshl_b32 s8, s9, 5
	s_add_i32 s9, s72, 0xffff87c0
	v_writelane_b32 v253, s43, 23
	s_lshr_b32 s44, s9, 10
	s_and_b32 s9, s9, 0x3c0
	s_and_b32 s8, s8, 0xffe0
	v_writelane_b32 v253, s9, 24
	s_lshl_b32 s9, s44, 3
	s_add_u32 s10, s70, s9
	s_addc_u32 s11, s71, 0
	v_writelane_b32 v253, s10, 25
	s_add_u32 s9, s20, 0x4380000
	s_addc_u32 s12, s21, 0
	v_writelane_b32 v253, s11, 26
	s_lshl_b64 s[10:11], s[44:45], 22
	v_writelane_b32 v253, s9, 27
	s_add_u32 s10, s9, s10
	v_writelane_b32 v253, s12, 28
	s_addc_u32 s11, s12, s11
	v_writelane_b32 v253, s10, 29
	s_and_b32 s9, s72, 0x7fc0
	s_mov_b64 s[40:41], 0x80
	v_writelane_b32 v253, s11, 30
	s_add_i32 s10, s9, 0xffff8fc0
	v_writelane_b32 v253, s10, 31
	s_load_dwordx2 s[10:11], s[70:71], 0xa8
	s_load_dwordx4 s[36:39], s[70:71], 0xc0
	s_waitcnt lgkmcnt(0)
; __device__ __forceinline__ TItem titem_get(const Args& a, int l, int it) {
;     unsigned char* ws = a.ws; TItem d;
;     constexpr int I_IN = 32 * 370, I_13 = 32 * 176, I_2 = 88 * 64, I_O = 32 * 64, I_BR = 16 * 64, I_UQ = 8 * 48;
;     int r = it; d.mode13 = false; d.gate8 = false;
;     if (r < I_IN) { const int kb = r / 370, nb = r % 370, n0 = nb * 32; d.W = a.in[I_WIN] + (size_t)l * DM * INW; d.K = DM; d.N = INW; d.WT = (bf16_t*)(ws + WS_WIN);
;         d.k0 = kb * 64; d.n0 = n0; d.dbase = n0 < 4096 ? n0 : (n0 < 5696 ? n0 + 6144 : n0 - 1600);
;         if (n0 >= 5696) { d.gate8 = true; d.dbase = n0 - 5696; d.WT = (bf16_t*)(ws + WS_WG8); }
;         return d; }
;     r -= I_IN;
;     if (r < 2 * I_13) { const int which = r / I_13; r -= which * I_13; const int kb = r / 176, nb = r % 176; d.W = a.in[which ? I_WFF3 : I_WFF1] + (size_t)l * DM * DFF; d.K = DM; d.N = DFF; d.WT = (bf16_t*)(ws + WS_W13);
;         d.k0 = kb * 64; d.n0 = nb * 32; d.dbase = 64 * nb + 16 * which; d.mode13 = true; return d; }
;     r -= 2 * I_13;
;     if (r < I_2) { const int kb = r / 64, nb = r % 64; d.W = a.in[I_WFF2] + (size_t)l * DFF * DM; d.K = DFF; d.N = DM; d.WT = (bf16_t*)(ws + WS_W2); d.k0 = kb * 64; d.n0 = nb * 32; d.dbase = nb * 32; return d; }
;     r -= I_2;
;     if (r < I_O) { const int kb = r / 64, nb = r % 64; d.W = a.in[I_WO] + (size_t)l * DM * DM; d.K = DM; d.N = DM; d.WT = (bf16_t*)(ws + WS_WO); d.k0 = kb * 64; d.n0 = nb * 32; d.dbase = nb * 32; return d; }
;     r -= I_O;
;     if (r < 3 * I_BR) { const int br = r / I_BR; r -= br * I_BR; const int kb = r / 64, nb = r % 64; d.W = a.in[I_WBRA + br] + (size_t)l * 1024 * DM; d.K = 1024; d.N = DM; d.WT = (bf16_t*)(ws + WS_WBR) + (size_t)br * 2048 * 1024;
;         d.k0 = kb * 64; d.n0 = nb * 32; d.dbase = nb * 32; return d; }
;     r -= 3 * I_BR;
;     if (r < I_UQ) { const int kb = r / 48, nb = r % 48; d.W = a.in[I_WUQ] + (size_t)l * 512 * 1536; d.K = 512; d.N = 1536; d.WT = (bf16_t*)(ws + WS_WUQ); d.k0 = kb * 64; d.n0 = nb * 32; d.dbase = nb * 32; return d; }
;     r -= I_UQ;
;     { const int kb = r / 64, nb = r % 64; d.W = a.in[I_WUKV] + (size_t)l * 512 * 2048; d.K = 512; d.N = 2048; d.WT = (bf16_t*)(ws + WS_WUKV); d.k0 = kb * 64; d.n0 = nb * 32; d.dbase = nb * 32; return d; }
; }
; __device__ __forceinline__ void convert_weights(const Args& a, int l, int gw, int NGW, int lane, LAS float* scr) {
	s_add_u32 s10, s10, 0x1000000
	s_addc_u32 s11, s11, 0
	v_writelane_b32 v253, s10, 32
	s_nop 1
	v_writelane_b32 v253, s11, 33
	s_add_u32 s10, s20, 0x4f80000
	s_addc_u32 s11, s21, 0
	v_writelane_b32 v253, s10, 34
	s_addk_i32 s9, 0xa5c0
	s_nop 0
	v_writelane_b32 v253, s11, 35
	s_add_u32 s10, s36, 0x2c00000
	v_writelane_b32 v253, s9, 36
	s_addc_u32 s11, s37, 0
	v_writelane_b32 v253, s10, 37
	s_nop 1
	v_writelane_b32 v253, s11, 38
	s_add_u32 s10, s20, 0x8380000
	s_addc_u32 s11, s21, 0
	s_add_i32 s9, s72, 0xffffd1c0
	v_writelane_b32 v253, s10, 39
	s_cmpk_gt_u32 s9, 0x15ff
	s_nop 0
	v_writelane_b32 v253, s11, 40
	s_cselect_b32 s10, 0xea00, 0
	s_cselect_b32 s11, 16, 0
	s_add_i32 s10, s10, s9
	s_sext_i32_i16 s12, s10
	s_mulk_i32 s12, 0xba3
	s_lshr_b32 s13, s12, 31
	s_ashr_i32 s12, s12, 19
	s_add_i32 s12, s12, s13
	s_mul_i32 s13, s12, 0xb0
	s_sub_i32 s10, s10, s13
	s_cmpk_lt_u32 s9, 0x1600
	s_sext_i32_i16 s9, s10
	s_movk_i32 s10, 0xb8
	s_cselect_b32 s10, 0xb0, s10
	s_add_u32 s36, s20, 0x5780000
	v_writelane_b32 v253, s10, 41
	s_addc_u32 s37, s21, 0
	v_writelane_b32 v253, s36, 42
	s_lshl_b32 s10, s9, 6
	s_or_b32 s10, s10, s11
	v_writelane_b32 v253, s37, 43
	s_add_i32 s62, s62, s72
	v_writelane_b32 v253, s10, 44
	s_lshr_b32 s10, s62, 31
	s_ashr_i32 s11, s62, 8
	s_add_i32 s10, s11, s10
	s_sext_i32_i16 s11, s12
	s_lshl_b32 s11, s11, 6
	v_writelane_b32 v253, s11, 45
	s_lshl_b32 s9, s9, 5
	v_writelane_b32 v253, s9, 46
	s_mul_i32 s9, s10, 0x172
	s_sub_i32 s9, s72, s9
	s_lshl_b32 s13, s9, 5
	s_add_u32 s36, s84, 0x5c80000
	v_writelane_b32 v253, s76, 47
	s_addc_u32 s37, s85, 0
	s_lshl_b32 s10, s10, 6
	v_writelane_b32 v253, s77, 48
	v_writelane_b32 v253, s78, 49
	v_writelane_b32 v253, s79, 50
	v_writelane_b32 v253, s80, 51
	v_writelane_b32 v253, s81, 52
	v_writelane_b32 v253, s82, 53
	v_writelane_b32 v253, s83, 54
	v_writelane_b32 v253, s84, 55
	v_writelane_b32 v253, s85, 56
	v_writelane_b32 v253, s86, 57
	v_writelane_b32 v253, s87, 58
	v_writelane_b32 v253, s88, 59
	v_writelane_b32 v253, s89, 60
	v_writelane_b32 v253, s90, 61
	v_writelane_b32 v253, s91, 62
	v_writelane_b32 v253, s36, 63
	s_cmpk_lt_u32 s9, 0xb2
	s_mov_b64 s[84:85], s[28:29]
	v_writelane_b32 v250, s37, 0
	v_writelane_b32 v250, s10, 1
	s_movk_i32 s10, 0x1800
	s_cselect_b32 s10, s10, 0xfffff9c0
	s_cmpk_gt_i32 s9, 0x7f
	s_cselect_b32 s12, s10, 0
	s_cmpk_gt_i32 s9, 0xb1
	s_cselect_b64 s[28:29], -1, 0
	s_and_b64 s[10:11], s[28:29], exec
	s_mov_b32 s9, 0x35c00000
	s_cselect_b32 s9, s9, 0x1100000
	s_add_u32 s10, s20, s9
	s_addc_u32 s11, s21, 0
	v_writelane_b32 v250, s10, 2
	s_mov_b32 s86, s23
	s_load_dwordx2 s[80:81], s[70:71], 0xd8
	v_writelane_b32 v250, s11, 3
	v_writelane_b32 v250, s28, 4
	s_and_b64 s[10:11], s[28:29], exec
	s_cselect_b32 s9, 0xffffe9c0, s12
	v_writelane_b32 v250, s29, 5
	s_add_i32 s9, s9, s13
	v_writelane_b32 v250, s13, 6
	s_add_u32 s10, s20, 0x4180000
	v_writelane_b32 v250, s9, 7
	s_addc_u32 s11, s21, 0
	v_writelane_b32 v250, s10, 8
	s_mul_i32 s9, s18, 0x41
	s_mov_b32 s87, s24
	v_writelane_b32 v250, s11, 9
	s_add_u32 s10, s20, 0x4000000
	s_addc_u32 s11, s21, 0
	s_cmp_lt_i32 s18, 0
	s_cselect_b32 s0, s9, s0
	s_add_i32 s0, s0, s15
	s_ashr_i32 s9, s0, 31
	s_lshr_b32 s9, s9, 26
	v_writelane_b32 v250, s10, 10
	s_add_i32 s9, s0, s9
	s_mov_b32 s88, s26
	v_writelane_b32 v250, s11, 11
	s_and_b32 s10, s9, 0xffc0
	s_sub_i32 s0, s0, s10
	s_bfe_i32 s10, s0, 0x80000
	s_bfe_u32 s10, s10, 0x3000c
	s_add_i32 s10, s0, s10
	s_and_b32 s11, s10, 0xf8
	s_sub_i32 s0, s0, s11
	s_ashr_i32 s9, s9, 6
	s_lshl_b32 s9, s9, 3
	s_sext_i32_i8 s0, s0
	s_bfe_i32 s10, s10, 0x80000
	s_add_i32 s12, s9, s0
	s_sext_i32_i16 s10, s10
	s_ashr_i32 s13, s12, 31
	s_ashr_i32 s9, s10, 3
	s_lshr_b32 s0, s10, 3
	s_lshl_b64 s[10:11], s[12:13], 20
	s_add_u32 s28, s66, s10
	s_addc_u32 s29, s67, s11
	s_bfe_i64 s[10:11], s[0:1], 0x100000
	s_lshl_b64 s[10:11], s[10:11], 20
	v_writelane_b32 v250, s15, 12
	s_add_u32 s10, s19, s10
	v_writelane_b32 v250, s19, 13
	s_addc_u32 s11, s22, s11
	v_writelane_b32 v250, s22, 14
	s_add_u32 s22, s10, 0x80000
	s_addc_u32 s23, s11, 0
	v_writelane_b32 v250, s22, 15
	s_brev_b32 s0, 32
	v_readlane_b32 s82, v251, 12
	v_writelane_b32 v250, s23, 16
	s_add_u32 s22, s28, 0x80000
	v_writelane_b32 v250, s28, 17
	s_addc_u32 s23, s29, 0
	s_mov_b32 s91, 0x2aaaaaab
	v_writelane_b32 v250, s29, 18
	v_writelane_b32 v250, s22, 19
	s_movk_i32 s76, 0x1000
	s_mov_b32 s77, 0x800000
	v_writelane_b32 v250, s23, 20
	s_add_u32 s22, s10, 0x80080
	v_writelane_b32 v250, s10, 21
	s_addc_u32 s23, s11, 0
	s_mov_b32 s79, 0x42b504f3
	v_writelane_b32 v250, s11, 22
	v_writelane_b32 v250, s22, 23
	s_and_b64 s[10:11], s[4:5], exec
	s_cselect_b32 s11, s35, s31
	v_writelane_b32 v250, s23, 24
	v_writelane_b32 v250, s30, 25
	s_cselect_b32 s0, s0, 0x4180000
	s_brev_b32 s36, 63
	v_writelane_b32 v250, s31, 26
	v_writelane_b32 v250, s34, 27
	s_cselect_b32 s10, s34, s30
	s_mov_b32 s37, 0xfc800000
	v_writelane_b32 v250, s35, 28
	v_writelane_b32 v250, s10, 29
	s_waitcnt lgkmcnt(0)
; #define LAS __attribute__((address_space(3)))
; #define GSYNC() xcd_barrier(xb)
; __device__ __forceinline__ void xcd_barrier_complete(unsigned* bar, unsigned x, unsigned& nloc, unsigned& nx) {
;     const unsigned G = gridDim.x * gridDim.y * gridDim.z;
; __global__ void __launch_bounds__(512, 2) fwd_megakernel(Args a) {
;     extern __shared__ __attribute__((aligned(16))) unsigned char lds[];
;     cg::grid_group grid = cg::this_grid();
;     const int tid = threadIdx.x, lane = tid & 63, wave = __builtin_amdgcn_readfirstlane(tid >> 6);
;     const int G = gridDim.x, bid = blockIdx.x;
;     const int vcu = (G % 8 == 0) ? (bid % 8) * (G / 8) + bid / 8 : bid;
;     const int gw = vcu * 8 + wave, NGW = G * 8;
;     unsigned char* ws = a.ws;
;     LAS unsigned char* ldsl = (LAS unsigned char*)lds;
;     LAS float* scr = (LAS float*)(ldsl + wave * 16384);
;     float* mod = (float*)(ws + WS_MOD); float* CX = (float*)(ws + WS_CX);
;     bf16_t* H = (bf16_t*)(ws + WS_H); bf16_t* Z = (bf16_t*)(ws + WS_Z); bf16_t* QC = (bf16_t*)(ws + WS_H); bf16_t* KVC = (bf16_t*)(ws + WS_KVC);
;     bf16_t* Y = (bf16_t*)(ws + WS_KVC); bf16_t* O = (bf16_t*)(ws + WS_O); bf16_t* T = (bf16_t*)(ws + WS_T); bf16_t* U = (bf16_t*)(ws + WS_U); bf16_t* TP = (bf16_t*)(ws + WS_TP);
;     unsigned* barw = (unsigned*)(ws + WS_BAR);
;     volatile LAS unsigned* bst = (volatile LAS unsigned*)(ldsl + 131072 + 64);
;     if (bid == 0) for (int i = tid; i < XCD_BAR_WORDS; i += 512) barw[i] = 0u;
;     if (tid < 2) bst[tid] = 0u;
;     __syncthreads();
;     mod_phase(a, lds, bid, G, tid);
;     convert_weights(a, 0, gw, NGW, lane, scr);
;     grid.sync();
;     const XcdBarrier xb = xcd_barrier_post(barw, bst);
;     ...
;     row_phase<false, true>(bid, G, MTOT, a.in[I_X], a.in[I_CTX], nullptr, nullptr, nullptr, nullptr, nullptr, 0, nullptr, a.in[I_GPRE1], mod, 0, 2048, H, ws + WS_H8, lds);
;     GSYNC();
;     for (int l = 0; l < 2; ++l) {
	s_mul_i32 s35, s81, s80
	s_mul_i32 s89, s35, s54
	v_writelane_b32 v250, s11, 30
	s_add_u32 s10, s20, s0
	s_addc_u32 s11, s21, 0
	v_writelane_b32 v250, s10, 31
	s_and_b64 s[4:5], s[4:5], exec
	s_movk_i32 s0, 0x600
	v_writelane_b32 v250, s11, 32
	s_cselect_b32 s44, s0, 0x800
	s_cselect_b32 s0, s7, s6
	v_writelane_b32 v250, s0, 33
	v_writelane_b32 v250, s27, 34
	s_cselect_b32 s0, s8, s27
	v_writelane_b32 v250, s0, 35
	v_writelane_b32 v250, s18, 36
	s_lshr_b32 s0, s18, 31
	v_writelane_b32 v250, s0, 37
	s_mov_b32 s4, s12
	v_writelane_b32 v250, s4, 38
	s_mul_hi_i32 s0, s12, 0x2c0000
	s_mov_b32 s81, s48
	v_writelane_b32 v250, s5, 39
	s_mul_i32 s4, s12, 0x2c0000
	s_add_u32 s6, s16, s4
	v_writelane_b32 v250, s16, 40
	s_addc_u32 s7, s17, s0
	s_mul_i32 s4, s9, 0x2c0000
	s_mul_hi_i32 s0, s9, 0x2c0000
	s_add_u32 s4, s25, s4
	v_writelane_b32 v250, s17, 41
	s_addc_u32 s5, s26, s0
	v_writelane_b32 v250, s9, 42
	s_add_u32 s8, s4, 0x160000
	v_writelane_b32 v250, s25, 43
	s_addc_u32 s9, s5, 0
	v_writelane_b32 v250, s8, 44
	v_readlane_b32 s0, v251, 11
	s_brev_b32 s48, 63
	v_writelane_b32 v250, s9, 45
	s_add_u32 s8, s6, 0x160000
	v_writelane_b32 v250, s6, 46
	s_addc_u32 s9, s7, 0
	s_mov_b32 s35, 0x5040100
	v_writelane_b32 v250, s7, 47
	v_writelane_b32 v250, s8, 48
	s_add_u32 s6, s4, 0x160080
	s_mov_b32 s78, 0xfd801000
	v_writelane_b32 v250, s9, 49
	v_writelane_b32 v250, s4, 50
	s_addc_u32 s7, s5, 0
	s_cmp_lt_i32 s0, s97
	v_writelane_b32 v250, s5, 51
	v_writelane_b32 v250, s6, 52
	s_cselect_b64 s[4:5], -1, 0
	s_lshl_b32 s0, s55, 1
	v_writelane_b32 v250, s7, 53
	v_writelane_b32 v250, s4, 54
	s_mov_b64 s[6:7], s[38:39]
	s_mov_b32 s34, 0xe1581000
	v_writelane_b32 v250, s5, 55
	s_lshl_b32 s4, s14, 4
	s_add_i32 s0, s4, s0
	v_writelane_b32 v250, s0, 56
	s_lshl_b32 s0, s80, 4
	v_writelane_b32 v250, s0, 57
	s_add_u32 s0, s20, 0x28202100
	v_writelane_b32 v250, s0, 58
	s_addc_u32 s0, s21, 0
	v_writelane_b32 v250, s0, 59
	s_lshl_b32 s0, s14, 5
	s_lshl_b32 s90, s80, 5
	v_writelane_b32 v250, s0, 60
	s_add_u32 s0, s20, 0xe187000
	v_writelane_b32 v250, s0, 61
	s_addc_u32 s0, s21, 0
	v_writelane_b32 v250, s0, 62
	s_add_u32 s0, s20, 0xe182800
	v_writelane_b32 v249, s20, 0
	v_writelane_b32 v250, s0, 63
	s_addc_u32 s0, s21, 0
	v_writelane_b32 v249, s21, 1
	v_writelane_b32 v249, s0, 2
	s_add_u32 s4, s38, 0x1000
	v_writelane_b32 v249, s4, 3
	s_mov_b32 s38, 0x42ddb3d8
	s_mov_b64 s[26:27], -1
	v_writelane_b32 v249, s5, 4
	v_writelane_b32 v249, s6, 5
	v_writelane_b32 v249, s7, 6
	s_addc_u32 s5, s39, 0
	v_writelane_b32 v249, s4, 7
	s_add_i32 s0, 0, 0x20040
	v_readlane_b32 s6, v251, 8
	v_writelane_b32 v249, s5, 8
	v_writelane_b32 v249, s0, 9
	s_add_i32 s0, 0, 0x20044
	v_writelane_b32 v249, s0, 10
	s_add_i32 s0, 0, 0x15000
	v_writelane_b32 v249, s0, 11
	s_add_i32 s0, 0, 0x14800
	v_writelane_b32 v249, s0, 12
	v_writelane_b32 v249, s72, 13
	s_add_i32 s6, s6, s72
	v_writelane_b32 v249, s6, 14
	s_mov_b32 s6, 0
	s_mov_b64 s[4:5], s[70:71]
	v_writelane_b32 v249, s6, 15
	s_load_dwordx2 s[42:43], s[4:5], 0x0
	v_writelane_b32 v249, s4, 17
	s_load_dwordx2 s[50:51], s[4:5], 0x10
	s_movk_i32 s70, 0x4000
	v_writelane_b32 v249, s5, 18
	v_writelane_b32 v249, s44, 19
	s_movk_i32 s71, 0x5c80
	s_movk_i32 s39, 0x3fff
	v_writelane_b32 v249, s45, 20
	v_writelane_b32 v249, s33, 21
	v_writelane_b32 v249, s57, 22
	v_writelane_b32 v249, s97, 23
	v_writelane_b32 v249, s92, 24
	v_writelane_b32 v249, s84, 25
	s_mov_b32 s0, 0xfc801000
	s_mov_b64 s[54:55], 0x100
	v_writelane_b32 v249, s85, 26
	v_writelane_b32 v249, s86, 27
	v_writelane_b32 v249, s87, 28
	v_writelane_b32 v249, s88, 29
	v_writelane_b32 v249, s89, 30
	s_mov_b64 s[22:23], 0x180
	s_mov_b32 s62, 0x3a000000
	s_mov_b32 s49, -1
	v_readlane_b32 s83, v251, 13
	v_writelane_b32 v249, s81, 31
	v_writelane_b32 v249, s90, 32
	s_branch .LBB0_209

;     __device__ __forceinline__ bool next(int i, Unit& u) const { const int L = i * G + c; if (L >= 256) return false; u.sub = L & 3; const int t = L >> 2; u.pm = 64 + (t >> 3); u.pn = t & 7; return true; }
;     __device__ __forceinline__ bool next(int i, Unit& u) const {
;         int L = i * G + c;
;         if (L < n0) { u.sub = 0; u.pm = L / nN0; u.pn = L - u.pm * nN0; return true; }
;         L -= n0; if (L >= n1) return false;
;         u.sub = 1; u.pm = L / nN1; u.pn = L - u.pm * nN1; return true;
;     }
; __global__ void __launch_bounds__(512, 2) fwd_megakernel(Args a) {
;     ...
;         { pg8::DualSched S; S.G = G; S.c = bid; S.n0 = (MTOT / 256) * 6; S.n1 = (MTOT / 256) * 8; S.nN0 = 6; S.nN1 = 8;
;           S.A0 = (const char*)(Z + ZC_CQ); S.A1 = (const char*)(Z + ZC_CKV); S.B0 = (const char*)(ws + WS_WUQ); S.B1 = (const char*)(ws + WS_WUKV);
;           S.aT = (size_t)256 * LDZ * 2; S.bT = (size_t)256 * 512 * 2;
;           pg8::EpiQKV E{QC, KVC, LDQC, LDKVC}; pg8::gemm_phase(ldsl, LDZ, 512, 512, S, E); }
.LBB0_426:
	s_add_i32 s57, s57, 1
	s_mul_i32 s11, s57, s80
	v_readlane_b32 s4, v251, 0
	s_add_i32 s11, s11, s4
	s_cmpk_gt_i32 s11, 0x1af
	s_mov_b64 s[4:5], -1
	s_cbranch_scc0 .LBB0_429
	s_add_i32 s16, s11, 0xfffffe50
	s_mov_b64 s[4:5], 0
	s_cmpk_gt_u32 s16, 0x23f
	s_mov_b64 s[14:15], 0
	s_cbranch_scc1 .LBB0_429
	s_lshr_b32 s74, s16, 3
	s_and_b32 s10, s11, 7
	s_mov_b32 s75, 1
	s_mov_b64 s[14:15], -1
